# attention loop: score accumulators initialised with 64-bit moves (14 fewer VALU per sub-tile)
# speedup vs baseline: 1.0139x; 1.0048x over previous
; #define LAS __attribute__((address_space(3)))
; __device__ __forceinline__ void dattn_unit(LAS unsigned char* lds, int b, int h, int qb, const bf16* Q, const bf16* K, const bf16* V, bf16* YB, float lam, const float* subg, float oml, int tid) {
;     ...
;         if (t + 1 < NT) { const size_t adv = (size_t)(t + 1) * 64 * 1024; kr0 = *(const v4u*)(kg + adv); kr1 = *(const v4u*)(kg + adv + 64); vr0 = *(const v4u*)(vg + adv); vr1 = *(const v4u*)(vg + adv + 8); }
;         const LAS bf16* Ks = (const LAS bf16*)(lds + (t & 1) * AT_BUF + AT_KS); const LAS bf16* Vt = (const LAS bf16*)(lds + (t & 1) * AT_BUF + AT_VT);
;         const int kvbase = t * 64;
;         if (kvbase <= qmax) {
;     ...
; #pragma unroll
;         for (int sub = 0; sub < 2; ++sub) {
;             if (kvbase + 32 * sub > qmax) continue;
;             const bool need_bm = kvbase + 32 * sub + 31 + 113 > qmin;
;             LAS bf16x8* qsp = qs; asm volatile("" : "+v"(qsp));
;             f32x16 s0, s1;
; #pragma unroll
;             for (int r = 0; r < 16; ++r) { s0[r] = -mref[0]; s1[r] = -mref[1]; }
;             {
;                 const LAS bf16* kp = Ks + (32 * sub + ql) * 72 + hi * 8;
;                 bf16x8 ka = *(const LAS bf16x8*)kp, kb = *(const LAS bf16x8*)(kp + 64 * 72), qa = qsp[0], qb = qsp[4 * 64];
;                 __builtin_amdgcn_sched_group_barrier(0x100, 4, 0);
; #pragma unroll
;                 for (int ks = 0; ks < 4; ++ks) { bf16x8 ka2 = ka, kb2 = kb, qa2 = qa, qb2 = qb;
;                     if (ks < 3) { ka2 = *(const LAS bf16x8*)(kp + (ks + 1) * 16); kb2 = *(const LAS bf16x8*)(kp + 64 * 72 + (ks + 1) * 16); qa2 = qsp[(ks + 1) * 64]; qb2 = qsp[(4 + ks + 1) * 64];
;                         __builtin_amdgcn_sched_group_barrier(0x100, 4, 0); }
;                     s0 = __builtin_amdgcn_mfma_f32_32x32x16_bf16(ka, qa, s0, 0, 0, 0);
;                     s1 = __builtin_amdgcn_mfma_f32_32x32x16_bf16(kb, qb, s1, 0, 0, 0);
;                     __builtin_amdgcn_sched_group_barrier(0x008, 2, 0);
;                     ka = ka2; kb = kb2; qa = qa2; qb = qb2; }
;             }
.LBB0_227:
	v_lshl_add_u64 v[128:129], v[184:185], 0, s[16:17]
	s_mov_b32 s18, 0x1b020000
	v_add_co_u32_e32 v128, vcc, s18, v128
	v_lshl_add_u64 v[130:131], v[182:183], 0, s[16:17]
	s_nop 0
	v_addc_co_u32_e32 v129, vcc, 0, v129, vcc
	global_load_dwordx4 v[168:171], v[128:129], off
	global_load_dwordx4 v[172:175], v[128:129], off offset:128
	v_add_co_u32_e32 v128, vcc, 0xb020000, v130
	s_add_i32 s18, s58, 0xffffff50
	s_nop 0
	v_addc_co_u32_e32 v129, vcc, 0, v131, vcc
	global_load_dwordx4 v[164:167], v[128:129], off
	global_load_dwordx4 v[160:163], v[128:129], off offset:16
	s_cmp_gt_i32 s18, s35
	s_cbranch_scc1 .LBB0_226
	s_bitcmp1_b32 s59, 0
	s_cselect_b32 s18, 0x9000, 0
	s_add_i32 s38, s18, 0
	v_add_u32_e32 v136, s38, v208
	v_mov_b32_e32 v212, v189
	v_add_u32_e32 v199, v136, v192
	ds_read_b128 v[138:141], v199
	ds_read_b128 v[200:203], v199 offset:9216
	ds_read_b128 v[204:207], v212
	ds_read_b128 v[218:221], v212 offset:4096
	v_xor_b32_e32 v144, 0x80000000, v190
	v_xor_b32_e32 v128, 0x80000000, v191
	v_mov_b32_e32 v145, v144
	v_mov_b64_e32 v[146:147], v[144:145]
	v_mov_b64_e32 v[148:149], v[144:145]
	v_mov_b64_e32 v[150:151], v[144:145]
	v_mov_b64_e32 v[152:153], v[144:145]
	v_mov_b64_e32 v[154:155], v[144:145]
	v_mov_b64_e32 v[156:157], v[144:145]
	v_mov_b64_e32 v[158:159], v[144:145]
	v_mov_b32_e32 v129, v128
	v_mov_b64_e32 v[130:131], v[128:129]
	v_mov_b64_e32 v[132:133], v[128:129]
	v_mov_b64_e32 v[134:135], v[128:129]
	v_mov_b64_e32 v[136:137], v[128:129]
	ds_read_b128 v[222:225], v199 offset:32
	ds_read_b128 v[226:229], v199 offset:9248
	ds_read_b128 v[230:233], v212 offset:1024
	ds_read_b128 v[234:237], v212 offset:5120
	s_waitcnt lgkmcnt(5)
	v_mfma_f32_32x32x16_bf16 v[144:159], v[138:141], v[204:207], v[144:159]
	v_mov_b64_e32 v[142:143], v[128:129]
	v_mov_b64_e32 v[138:139], v[128:129]
	v_mov_b64_e32 v[140:141], v[128:129]
	s_sub_i32 s18, s58, 32
	s_cmp_le_i32 s18, s31
	s_waitcnt lgkmcnt(4)
	v_mfma_f32_32x32x16_bf16 v[128:143], v[200:203], v[218:221], v[128:143]
	ds_read_b128 v[200:203], v199 offset:64
	ds_read_b128 v[204:207], v199 offset:9280
	ds_read_b128 v[218:221], v212 offset:2048
	ds_read_b128 v[238:241], v212 offset:6144
	s_waitcnt lgkmcnt(5)
	v_mfma_f32_32x32x16_bf16 v[144:159], v[222:225], v[230:233], v[144:159]
	s_waitcnt lgkmcnt(4)
	v_mfma_f32_32x32x16_bf16 v[128:143], v[226:229], v[234:237], v[128:143]
	ds_read_b128 v[222:225], v199 offset:96
	ds_read_b128 v[226:229], v199 offset:9312
	ds_read_b128 v[230:233], v212 offset:3072
	ds_read_b128 v[234:237], v212 offset:7168
	s_waitcnt lgkmcnt(5)
	v_mfma_f32_32x32x16_bf16 v[144:159], v[200:203], v[218:221], v[144:159]
	s_cbranch_scc0 .Lqk_diag0
	s_waitcnt lgkmcnt(1)
	v_mfma_f32_32x32x16_bf16 v[144:159], v[222:225], v[230:233], v[144:159]
	v_add3_u32 v219, s38, v193, v192
	ds_read_b128 v[212:215], v219 offset:32256
	ds_read_b128 v[220:223], v219 offset:18432
	v_mfma_f32_32x32x16_bf16 v[128:143], v[204:207], v[238:241], v[128:143]
	s_waitcnt lgkmcnt(2)
	v_mfma_f32_32x32x16_bf16 v[128:143], v[226:229], v[234:237], v[128:143]
	ds_read_b128 v[228:231], v219 offset:23040
	ds_read_b128 v[232:235], v219 offset:23072
	ds_read_b128 v[236:239], v219 offset:27648
	ds_read_b128 v[240:243], v219 offset:27680
	s_nop 1

; #define LAS __attribute__((address_space(3)))
; __device__ __forceinline__ void dattn_unit(LAS unsigned char* lds, int b, int h, int qb, const bf16* Q, const bf16* K, const bf16* V, bf16* YB, float lam, const float* subg, float oml, int tid) {
;     ...
;             if (kvbase + 32 * sub > qmax) continue;
;             const bool need_bm = kvbase + 32 * sub + 31 + 113 > qmin;
;             LAS bf16x8* qsp = qs; asm volatile("" : "+v"(qsp));
;             f32x16 s0, s1;
; #pragma unroll
;             for (int r = 0; r < 16; ++r) { s0[r] = -mref[0]; s1[r] = -mref[1]; }
;             {
;                 const LAS bf16* kp = Ks + (32 * sub + ql) * 72 + hi * 8;
;                 bf16x8 ka = *(const LAS bf16x8*)kp, kb = *(const LAS bf16x8*)(kp + 64 * 72), qa = qsp[0], qb = qsp[4 * 64];
;                 __builtin_amdgcn_sched_group_barrier(0x100, 4, 0);
; #pragma unroll
;                 for (int ks = 0; ks < 4; ++ks) { bf16x8 ka2 = ka, kb2 = kb, qa2 = qa, qb2 = qb;
;                     if (ks < 3) { ka2 = *(const LAS bf16x8*)(kp + (ks + 1) * 16); kb2 = *(const LAS bf16x8*)(kp + 64 * 72 + (ks + 1) * 16); qa2 = qsp[(ks + 1) * 64]; qb2 = qsp[(4 + ks + 1) * 64];
;                         __builtin_amdgcn_sched_group_barrier(0x100, 4, 0); }
;                     s0 = __builtin_amdgcn_mfma_f32_32x32x16_bf16(ka, qa, s0, 0, 0, 0);
;                     s1 = __builtin_amdgcn_mfma_f32_32x32x16_bf16(kb, qb, s1, 0, 0, 0);
;                     __builtin_amdgcn_sched_group_barrier(0x008, 2, 0);
;                     ka = ka2; kb = kb2; qa = qa2; qb = qb2; }
;             }
.LBB0_238:
	s_add_i32 s18, s58, 0xffffff70
	s_cmp_gt_i32 s18, s35
	s_cbranch_scc1 .LBB0_226
	v_mov_b32_e32 v242, v189
	ds_read_b128 v[138:141], v199 offset:4608
	ds_read_b128 v[204:207], v199 offset:13824
	ds_read_b128 v[218:221], v242
	ds_read_b128 v[222:225], v242 offset:4096
	v_xor_b32_e32 v144, 0x80000000, v190
	v_xor_b32_e32 v128, 0x80000000, v191
	v_mov_b32_e32 v145, v144
	v_mov_b64_e32 v[146:147], v[144:145]
	v_mov_b64_e32 v[148:149], v[144:145]
	v_mov_b64_e32 v[150:151], v[144:145]
	v_mov_b64_e32 v[152:153], v[144:145]
	v_mov_b64_e32 v[154:155], v[144:145]
	v_mov_b64_e32 v[156:157], v[144:145]
	v_mov_b64_e32 v[158:159], v[144:145]
	v_mov_b32_e32 v129, v128
	v_mov_b64_e32 v[130:131], v[128:129]
	v_mov_b64_e32 v[132:133], v[128:129]
	v_mov_b64_e32 v[134:135], v[128:129]
	v_mov_b64_e32 v[136:137], v[128:129]
	ds_read_b128 v[226:229], v199 offset:4640
	ds_read_b128 v[230:233], v199 offset:13856
	ds_read_b128 v[234:237], v242 offset:1024
	ds_read_b128 v[238:241], v242 offset:5120
	s_waitcnt lgkmcnt(5)
	v_mfma_f32_32x32x16_bf16 v[144:159], v[138:141], v[218:221], v[144:159]
	v_mov_b64_e32 v[142:143], v[128:129]
	v_mov_b64_e32 v[138:139], v[128:129]
	v_mov_b64_e32 v[140:141], v[128:129]
	s_cmp_le_i32 s58, s31
	s_waitcnt lgkmcnt(4)
	v_mfma_f32_32x32x16_bf16 v[128:143], v[204:207], v[222:225], v[128:143]
	ds_read_b128 v[204:207], v199 offset:4672
	ds_read_b128 v[218:221], v199 offset:13888
	ds_read_b128 v[222:225], v242 offset:2048
	ds_read_b128 v[212:215], v242 offset:6144
	s_waitcnt lgkmcnt(5)
	v_mfma_f32_32x32x16_bf16 v[144:159], v[226:229], v[234:237], v[144:159]
	s_waitcnt lgkmcnt(4)
	v_mfma_f32_32x32x16_bf16 v[128:143], v[230:233], v[238:241], v[128:143]
	ds_read_b128 v[226:229], v199 offset:4704
	ds_read_b128 v[230:233], v199 offset:13920
	ds_read_b128 v[234:237], v242 offset:3072
	ds_read_b128 v[238:241], v242 offset:7168
	s_waitcnt lgkmcnt(5)
	v_mfma_f32_32x32x16_bf16 v[144:159], v[204:207], v[222:225], v[144:159]
	s_cbranch_scc0 .Lqk_diag1
	s_waitcnt lgkmcnt(1)
	v_mfma_f32_32x32x16_bf16 v[144:159], v[226:229], v[234:237], v[144:159]
	v_add3_u32 v243, s38, v193, v192
	ds_read_b128 v[222:225], v243 offset:23104
	ds_read_b128 v[226:229], v243 offset:23136
	v_mfma_f32_32x32x16_bf16 v[128:143], v[218:221], v[212:215], v[128:143]
	s_waitcnt lgkmcnt(2)
	v_mfma_f32_32x32x16_bf16 v[128:143], v[230:233], v[238:241], v[128:143]
	ds_read_b128 v[230:233], v243 offset:27712
	ds_read_b128 v[234:237], v243 offset:27744
	ds_read_b128 v[238:241], v243 offset:32320
	ds_read_b128 v[212:215], v243 offset:18496
	ds_read_b128 v[200:203], v243 offset:18528
	s_nop 1
